# all grid syncs arrive on eight per-group sub-counters (at most 32 same-address atomics); global waits poll the eight words
# speedup vs baseline: 1.0188x; 1.0040x over previous
; __device__ __forceinline__ CArgs* get_args() { CArgs* p = (CArgs*)__builtin_amdgcn_kernarg_segment_ptr(); asm volatile("" : "+s"(p)); return p; }
; __global__ void __launch_bounds__(512, 2) hymba_fwd(Args A_unused) {
;     ...
;     const int wave0 = __builtin_amdgcn_readfirstlane(threadIdx.x >> 6);
;     ...
;     unsigned nsync = 0;
;     ...
;     { PHASE_IDS(); if (blk == 0 && tid == 0) __hip_atomic_store((unsigned*)(get_args()->ws + WS_CTL), 0u, __ATOMIC_RELAXED, __HIP_MEMORY_SCOPE_AGENT);
_Z9hymba_fwd4Args:
	s_load_dword s67, s[0:1], 0xe0
	s_mov_b64 s[68:69], s[0:1]
	v_and_b32_e32 v1, 0x3ff, v0
	s_add_u32 s6, s68, 0xe0
	v_readfirstlane_b32 s24, v1
	s_addc_u32 s7, s69, 0
	s_lshr_b32 s77, s24, 6
	s_mov_b32 s76, s2
	s_mov_b32 s0, s77
	v_mbcnt_lo_u32_b32 v2, -1, 0
	v_mbcnt_hi_u32_b32 v2, -1, v2
	s_waitcnt lgkmcnt(0)
	s_mov_b32 s2, s67
	v_lshl_add_u32 v3, s0, 6, v2
	s_mov_b32 s4, s76
	s_nop 0
	v_or_b32_e32 v2, s4, v3
	v_readfirstlane_b32 s3, v3
	v_cmp_eq_u32_e32 vcc, 0, v2
	s_and_saveexec_b64 s[0:1], vcc
	s_cbranch_execz .LBB0_2
	s_mov_b64 s[8:9], s[68:69]
	s_load_dwordx2 s[8:9], s[8:9], 0xd8
	v_mov_b32_e32 v2, 0
	s_waitcnt lgkmcnt(0)
	global_store_dword v2, v2, s[8:9] sc1
	global_store_dword v2, v2, s[8:9] offset:256 sc1
	global_store_dword v2, v2, s[8:9] offset:320 sc1
	global_store_dword v2, v2, s[8:9] offset:384 sc1
	global_store_dword v2, v2, s[8:9] offset:448 sc1
	global_store_dword v2, v2, s[8:9] offset:512 sc1
	global_store_dword v2, v2, s[8:9] offset:576 sc1
	global_store_dword v2, v2, s[8:9] offset:640 sc1
	global_store_dword v2, v2, s[8:9] offset:704 sc1
	global_store_dword v2, v2, s[8:9] offset:1024 sc1
	global_store_dword v2, v2, s[8:9] offset:1088 sc1
	global_store_dword v2, v2, s[8:9] offset:1152 sc1
	global_store_dword v2, v2, s[8:9] offset:1216 sc1
	global_store_dword v2, v2, s[8:9] offset:1280 sc1
	global_store_dword v2, v2, s[8:9] offset:1344 sc1
	global_store_dword v2, v2, s[8:9] offset:1408 sc1
	global_store_dword v2, v2, s[8:9] offset:1472 sc1

.LBB0_798:
	s_waitcnt vmcnt(0) lgkmcnt(0)
	s_waitcnt vmcnt(0)
	s_barrier
	v_mbcnt_lo_u32_b32 v0, -1, 0
	v_mbcnt_hi_u32_b32 v0, -1, v0
	s_nop 0
	v_cmp_eq_u32_e32 vcc, 0, v0
	s_and_b64 s[2:3], s[92:93], vcc
	s_and_saveexec_b64 s[0:1], s[2:3]
	s_cbranch_execz .LBB0_812
	s_mov_b64 s[2:3], s[68:69]
	s_load_dwordx2 s[2:3], s[2:3], 0xd8
	s_mov_b64 s[4:5], exec
	buffer_wbl2 sc1
	s_waitcnt lgkmcnt(0)
	s_waitcnt vmcnt(0)
	v_mbcnt_lo_u32_b32 v0, s4, 0
	v_mbcnt_hi_u32_b32 v0, s5, v0
	v_cmp_eq_u32_e32 vcc, 0, v0
	s_and_saveexec_b64 s[6:7], vcc
	s_cbranch_execz .LBB0_801
	s_bcnt1_i32_b64 s4, s[4:5]
	v_mov_b32_e32 v0, s4
	s_and_b32 s4, s76, 7
	s_lshl_b32 s4, s4, 6
	s_add_i32 s4, s4, 0x400
	s_add_u32 s4, s2, s4
	s_addc_u32 s5, s3, 0
	global_atomic_add v145, v0, s[4:5]
.LBB0_801:
	s_or_b64 exec, exec, s[6:7]
	v_readlane_b32 s4, v254, 1
	s_add_i32 s6, s4, 1
	s_lshl_b32 s6, s6, 5
	s_mov_b32 s7, 0x400000
	s_branch .LBB0_803

.LBB0_803:
	global_load_dword v0, v145, s[2:3] offset:1024 sc1
	global_load_dword v1, v145, s[2:3] offset:1088 sc1
	global_load_dword v2, v145, s[2:3] offset:1152 sc1
	global_load_dword v3, v145, s[2:3] offset:1216 sc1
	global_load_dword v4, v145, s[2:3] offset:1280 sc1
	global_load_dword v5, v145, s[2:3] offset:1344 sc1
	global_load_dword v6, v145, s[2:3] offset:1408 sc1
	global_load_dword v7, v145, s[2:3] offset:1472 sc1
	s_mov_b64 s[4:5], -1
	s_waitcnt vmcnt(0)
	v_min3_u32 v0, v0, v1, v2
	v_min3_u32 v3, v3, v4, v5
	v_min3_u32 v0, v0, v6, v7
	v_min_u32_e32 v0, v0, v3
	v_cmp_le_u32_e32 vcc, s6, v0
	s_cbranch_vccnz .LBB0_802
	s_sleep 2
	global_load_dword v0, v145, s[2:3] offset:1024 sc1
	global_load_dword v1, v145, s[2:3] offset:1088 sc1
	global_load_dword v2, v145, s[2:3] offset:1152 sc1
	global_load_dword v3, v145, s[2:3] offset:1216 sc1
	global_load_dword v4, v145, s[2:3] offset:1280 sc1
	global_load_dword v5, v145, s[2:3] offset:1344 sc1
	global_load_dword v6, v145, s[2:3] offset:1408 sc1
	global_load_dword v7, v145, s[2:3] offset:1472 sc1
	s_waitcnt vmcnt(0)
	v_min3_u32 v0, v0, v1, v2
	v_min3_u32 v3, v3, v4, v5
	v_min3_u32 v0, v0, v6, v7
	v_min_u32_e32 v0, v0, v3
	v_cmp_gt_u32_e32 vcc, s6, v0
	s_cbranch_vccz .LBB0_802
	s_sleep 2
	global_load_dword v0, v145, s[2:3] offset:1024 sc1
	global_load_dword v1, v145, s[2:3] offset:1088 sc1
	global_load_dword v2, v145, s[2:3] offset:1152 sc1
	global_load_dword v3, v145, s[2:3] offset:1216 sc1
	global_load_dword v4, v145, s[2:3] offset:1280 sc1
	global_load_dword v5, v145, s[2:3] offset:1344 sc1
	global_load_dword v6, v145, s[2:3] offset:1408 sc1
	global_load_dword v7, v145, s[2:3] offset:1472 sc1
	s_waitcnt vmcnt(0)
	v_min3_u32 v0, v0, v1, v2
	v_min3_u32 v3, v3, v4, v5
	v_min3_u32 v0, v0, v6, v7
	v_min_u32_e32 v0, v0, v3
	v_cmp_gt_u32_e32 vcc, s6, v0
	s_cbranch_vccz .LBB0_802
	s_sleep 2
	global_load_dword v0, v145, s[2:3] offset:1024 sc1
	global_load_dword v1, v145, s[2:3] offset:1088 sc1
	global_load_dword v2, v145, s[2:3] offset:1152 sc1
	global_load_dword v3, v145, s[2:3] offset:1216 sc1
	global_load_dword v4, v145, s[2:3] offset:1280 sc1
	global_load_dword v5, v145, s[2:3] offset:1344 sc1
	global_load_dword v6, v145, s[2:3] offset:1408 sc1
	global_load_dword v7, v145, s[2:3] offset:1472 sc1
	s_waitcnt vmcnt(0)
	v_min3_u32 v0, v0, v1, v2
	v_min3_u32 v3, v3, v4, v5
	v_min3_u32 v0, v0, v6, v7
	v_min_u32_e32 v0, v0, v3
	v_cmp_gt_u32_e32 vcc, s6, v0
	s_cbranch_vccz .LBB0_802
	s_sleep 2
	global_load_dword v0, v145, s[2:3] offset:1024 sc1
	global_load_dword v1, v145, s[2:3] offset:1088 sc1
	global_load_dword v2, v145, s[2:3] offset:1152 sc1
	global_load_dword v3, v145, s[2:3] offset:1216 sc1
	global_load_dword v4, v145, s[2:3] offset:1280 sc1
	global_load_dword v5, v145, s[2:3] offset:1344 sc1
	global_load_dword v6, v145, s[2:3] offset:1408 sc1
	global_load_dword v7, v145, s[2:3] offset:1472 sc1
	s_waitcnt vmcnt(0)
	v_min3_u32 v0, v0, v1, v2
	v_min3_u32 v3, v3, v4, v5
	v_min3_u32 v0, v0, v6, v7
	v_min_u32_e32 v0, v0, v3
	v_cmp_gt_u32_e32 vcc, s6, v0
	s_cbranch_vccz .LBB0_802
	s_sleep 2
	global_load_dword v0, v145, s[2:3] offset:1024 sc1
	global_load_dword v1, v145, s[2:3] offset:1088 sc1
	global_load_dword v2, v145, s[2:3] offset:1152 sc1
	global_load_dword v3, v145, s[2:3] offset:1216 sc1
	global_load_dword v4, v145, s[2:3] offset:1280 sc1
	global_load_dword v5, v145, s[2:3] offset:1344 sc1
	global_load_dword v6, v145, s[2:3] offset:1408 sc1
	global_load_dword v7, v145, s[2:3] offset:1472 sc1
	s_waitcnt vmcnt(0)
	v_min3_u32 v0, v0, v1, v2
	v_min3_u32 v3, v3, v4, v5
	v_min3_u32 v0, v0, v6, v7
	v_min_u32_e32 v0, v0, v3
	v_cmp_gt_u32_e32 vcc, s6, v0
	s_cbranch_vccz .LBB0_802
	s_sleep 2
	global_load_dword v0, v145, s[2:3] offset:1024 sc1
	global_load_dword v1, v145, s[2:3] offset:1088 sc1
	global_load_dword v2, v145, s[2:3] offset:1152 sc1
	global_load_dword v3, v145, s[2:3] offset:1216 sc1
	global_load_dword v4, v145, s[2:3] offset:1280 sc1
	global_load_dword v5, v145, s[2:3] offset:1344 sc1
	global_load_dword v6, v145, s[2:3] offset:1408 sc1
	global_load_dword v7, v145, s[2:3] offset:1472 sc1
	s_waitcnt vmcnt(0)
	v_min3_u32 v0, v0, v1, v2
	v_min3_u32 v3, v3, v4, v5
	v_min3_u32 v0, v0, v6, v7
	v_min_u32_e32 v0, v0, v3
	v_cmp_gt_u32_e32 vcc, s6, v0
	s_cbranch_vccz .LBB0_802
	s_sleep 2
	global_load_dword v0, v145, s[2:3] offset:1024 sc1
	global_load_dword v1, v145, s[2:3] offset:1088 sc1
	global_load_dword v2, v145, s[2:3] offset:1152 sc1
	global_load_dword v3, v145, s[2:3] offset:1216 sc1
	global_load_dword v4, v145, s[2:3] offset:1280 sc1
	global_load_dword v5, v145, s[2:3] offset:1344 sc1
	global_load_dword v6, v145, s[2:3] offset:1408 sc1
	global_load_dword v7, v145, s[2:3] offset:1472 sc1
	s_waitcnt vmcnt(0)
	v_min3_u32 v0, v0, v1, v2
	v_min3_u32 v3, v3, v4, v5
	v_min3_u32 v0, v0, v6, v7
	v_min_u32_e32 v0, v0, v3
	v_cmp_gt_u32_e32 vcc, s6, v0
	s_cbranch_vccz .LBB0_802
	s_add_i32 s7, s7, -8
	s_cmp_eq_u32 s7, 0
	s_cselect_b64 s[4:5], -1, 0
	s_sleep 2
	s_branch .LBB0_802

.LBB0_852:
	s_waitcnt vmcnt(0) lgkmcnt(0)
	s_barrier
	v_mbcnt_lo_u32_b32 v0, -1, 0
	v_mbcnt_hi_u32_b32 v0, -1, v0
	s_nop 0
	v_cmp_eq_u32_e32 vcc, 0, v0
	s_and_b64 s[2:3], s[92:93], vcc
	s_and_saveexec_b64 s[0:1], s[2:3]
	s_cbranch_execz .LBB0_866
	s_mov_b64 s[2:3], s[68:69]
	s_load_dwordx2 s[2:3], s[2:3], 0xd8
	s_mov_b64 s[4:5], exec
	buffer_wbl2 sc1
	s_waitcnt vmcnt(0) lgkmcnt(0)
	s_waitcnt vmcnt(0)
	v_mbcnt_lo_u32_b32 v0, s4, 0
	v_mbcnt_hi_u32_b32 v0, s5, v0
	v_cmp_eq_u32_e32 vcc, 0, v0
	s_and_saveexec_b64 s[6:7], vcc
	s_cbranch_execz .LBB0_855
	s_bcnt1_i32_b64 s4, s[4:5]
	v_mov_b32_e32 v0, s4
	s_and_b32 s4, s76, 7
	s_lshl_b32 s4, s4, 6
	s_add_i32 s4, s4, 0x400
	s_add_u32 s4, s2, s4
	s_addc_u32 s5, s3, 0
	global_atomic_add v145, v0, s[4:5]
.LBB0_855:
	s_or_b64 exec, exec, s[6:7]
	v_readlane_b32 s4, v254, 1
	s_add_i32 s6, s4, 2
	s_lshl_b32 s6, s6, 5
	s_mov_b32 s7, 0x400000
	s_branch .LBB0_857

; __global__ void __launch_bounds__(512, 2) hymba_fwd(Args A_unused) {
;     ...
;             __syncthreads();
.LBB0_1284:
	s_barrier
	s_waitcnt vmcnt(0) lgkmcnt(0)
	s_barrier
	v_mbcnt_lo_u32_b32 v0, -1, 0
	v_mbcnt_hi_u32_b32 v0, -1, v0
	s_nop 0
	v_cmp_eq_u32_e32 vcc, 0, v0
	s_and_b64 s[2:3], s[92:93], vcc
	s_and_saveexec_b64 s[0:1], s[2:3]
	s_cbranch_execz .LBB0_1298
	s_mov_b64 s[2:3], s[68:69]
	s_load_dwordx2 s[2:3], s[2:3], 0xd8
	s_mov_b64 s[4:5], exec
	buffer_wbl2 sc1
	s_waitcnt vmcnt(0) lgkmcnt(0)
	s_waitcnt vmcnt(0)
	v_mbcnt_lo_u32_b32 v0, s4, 0
	v_mbcnt_hi_u32_b32 v0, s5, v0
	v_cmp_eq_u32_e32 vcc, 0, v0
	s_and_saveexec_b64 s[6:7], vcc
	s_cbranch_execz .LBB0_1287
	s_bcnt1_i32_b64 s4, s[4:5]
	v_mov_b32_e32 v0, s4
	s_and_b32 s4, s76, 7
	s_lshl_b32 s4, s4, 6
	s_add_i32 s4, s4, 0x400
	s_add_u32 s4, s2, s4
	s_addc_u32 s5, s3, 0
	global_atomic_add v145, v0, s[4:5]
.LBB0_1287:
	s_or_b64 exec, exec, s[6:7]
	v_readlane_b32 s4, v254, 1
	s_add_i32 s6, s4, 3
	s_lshl_b32 s6, s6, 5
	s_mov_b32 s7, 0x400000
	s_branch .LBB0_1289

.LBB0_1322:
	s_waitcnt vmcnt(0) lgkmcnt(0)
	s_barrier
	v_mbcnt_lo_u32_b32 v0, -1, 0
	v_mbcnt_hi_u32_b32 v0, -1, v0
	s_nop 0
	v_cmp_eq_u32_e32 vcc, 0, v0
	s_and_b64 s[2:3], s[92:93], vcc
	s_and_saveexec_b64 s[0:1], s[2:3]
	v_readlane_b32 s12, v254, 15
	v_readlane_b32 s13, v254, 16
	s_cbranch_execz .LBB0_1336
	s_mov_b64 s[2:3], s[68:69]
	s_load_dwordx2 s[2:3], s[2:3], 0xd8
	s_mov_b64 s[4:5], exec
	buffer_wbl2 sc1
	s_waitcnt vmcnt(0) lgkmcnt(0)
	s_waitcnt vmcnt(0)
	v_mbcnt_lo_u32_b32 v0, s4, 0
	v_mbcnt_hi_u32_b32 v0, s5, v0
	v_cmp_eq_u32_e32 vcc, 0, v0
	s_and_saveexec_b64 s[6:7], vcc
	s_cbranch_execz .LBB0_1325
	s_bcnt1_i32_b64 s4, s[4:5]
	v_mov_b32_e32 v0, s4
	s_and_b32 s4, s76, 7
	s_lshl_b32 s4, s4, 6
	s_add_i32 s4, s4, 0x400
	s_add_u32 s4, s2, s4
	s_addc_u32 s5, s3, 0
	global_atomic_add v145, v0, s[4:5]

.LBB0_1378:
	s_waitcnt vmcnt(0) lgkmcnt(0)
	s_waitcnt lgkmcnt(0)
	s_barrier
	v_mbcnt_lo_u32_b32 v0, -1, 0
	v_mbcnt_hi_u32_b32 v0, -1, v0
	s_nop 0
	v_cmp_eq_u32_e32 vcc, 0, v0
	s_and_b64 s[2:3], s[92:93], vcc
	s_and_saveexec_b64 s[0:1], s[2:3]
	s_cbranch_execz .LBB0_1392
	s_mov_b64 s[2:3], s[68:69]
	s_load_dwordx2 s[2:3], s[2:3], 0xd8
	s_mov_b64 s[4:5], exec
	buffer_wbl2 sc1
	s_waitcnt vmcnt(0) lgkmcnt(0)
	s_waitcnt vmcnt(0)
	v_mbcnt_lo_u32_b32 v0, s4, 0
	v_mbcnt_hi_u32_b32 v0, s5, v0
	v_cmp_eq_u32_e32 vcc, 0, v0
	s_and_saveexec_b64 s[6:7], vcc
	s_cbranch_execz .LBB0_1381
	s_bcnt1_i32_b64 s4, s[4:5]
	v_mov_b32_e32 v0, s4
	s_and_b32 s4, s76, 7
	s_lshl_b32 s4, s4, 6
	s_add_i32 s4, s4, 0x400
	s_add_u32 s4, s2, s4
	s_addc_u32 s5, s3, 0
	global_atomic_add v145, v0, s[4:5]

; __global__ void __launch_bounds__(512, 2) hymba_fwd(Args A_unused) {
;     ...
;         FAST_SYNC();
.LBB0_1510:
	s_waitcnt vmcnt(0) lgkmcnt(0)
	s_waitcnt lgkmcnt(0)
	s_barrier
	v_readlane_b32 s0, v254, 1
	v_mbcnt_lo_u32_b32 v0, -1, 0
	v_mbcnt_hi_u32_b32 v0, -1, v0
	s_add_i32 s0, s0, 7
	v_cmp_eq_u32_e32 vcc, 0, v0
	s_and_b64 s[2:3], s[92:93], vcc
	v_writelane_b32 v254, s0, 1
	s_and_saveexec_b64 s[0:1], s[2:3]
	s_cbranch_execz .LBB0_347
	s_mov_b64 s[2:3], s[68:69]
	s_load_dwordx2 s[2:3], s[2:3], 0xd8
	s_mov_b64 s[4:5], exec
	buffer_wbl2 sc1
	s_waitcnt vmcnt(0) lgkmcnt(0)
	s_waitcnt vmcnt(0)
	v_mbcnt_lo_u32_b32 v0, s4, 0
	v_mbcnt_hi_u32_b32 v0, s5, v0
	v_cmp_eq_u32_e32 vcc, 0, v0
	s_and_saveexec_b64 s[6:7], vcc
	s_cbranch_execz .LBB0_1513
	s_bcnt1_i32_b64 s4, s[4:5]
	v_mov_b32_e32 v0, s4
	s_and_b32 s4, s76, 7
	s_lshl_b32 s4, s4, 6
	s_add_i32 s4, s4, 0x400
	s_add_u32 s4, s2, s4
	s_addc_u32 s5, s3, 0
	global_atomic_add v145, v0, s[4:5]
.LBB0_1513:
	s_or_b64 exec, exec, s[6:7]
	v_readlane_b32 s4, v254, 1
	s_lshl_b32 s6, s4, 5
	s_mov_b32 s7, 0x400000
	s_branch .LBB0_1515
